# phase 8 out-projection prompt tiles also on the 8-phase 256x256 tile engine (NH=8 Horner-folded rstd, residual X1, f32 LDS-staged epilogue)
# speedup vs baseline: 1.0641x; 1.0322x over previous
; template <int EPI>
; __device__ void gemm8_phase(const Params& p, const u16* __restrict__ A, const u16* __restrict__ Bt, const int K, const int nN,
;                             unsigned char* smem, const int rep) {
;     ...
;   const int nM = T_TOK / BM8, nwg = nM * nN;
;   const int wid = (int)p.wv, lane = (int)p.tidx & 63, wr = wid >> 2, wc = wid & 3, fr = lane & 15, fq = lane >> 4;
;   const int nt = K / BK8;
;   const __amdgpu_buffer_rsrc_t rsrc_A = __builtin_amdgcn_make_buffer_rsrc((void*)A, (short)0, T_TOK * K * 2, 0x00020000);
;   const __amdgpu_buffer_rsrc_t rsrc_Bt = __builtin_amdgcn_make_buffer_rsrc((void*)Bt, (short)0, nN * 256 * K * 2, 0x00020000);
;   int voff0, voff1;
;   {
;     int r_, c_;
;     stage_rc((int)p.tidx * 16, r_, c_);
;     voff0 = (r_ * K + c_) * 2;
;     stage_rc((int)p.tidx * 16 + 8192, r_, c_);
;     voff1 = (r_ * K + c_) * 2;
;   }
.LBB0_2005:
	s_cmp_lt_i32 s86, 9
	s_cselect_b64 s[0:1], -1, 0
	s_cmp_gt_i32 s88, 7
	s_cselect_b64 s[2:3], -1, 0
	s_and_b64 s[0:1], s[0:1], s[2:3]
	s_andn2_b64 vcc, exec, s[0:1]
	s_cbranch_vccnz .LBB0_2196
	s_mov_b32 s8, s84
	s_mov_b32 s22, s85
	v_mbcnt_lo_u32_b32 v0, -1, 0
	v_readlane_b32 s2, v255, 6
	v_mbcnt_hi_u32_b32 v195, -1, v0
	s_nop 0
	v_lshl_add_u32 v252, s2, 6, v195
	v_bfe_i32 v1, v252, 27, 1
	v_lshlrev_b32_e32 v138, 4, v252
	v_lshrrev_b32_e32 v1, 22, v1
	v_add_u32_e32 v1, v138, v1
	v_and_b32_e32 v1, 0xfffffc00, v1
	v_sub_u32_e32 v1, v138, v1
	v_lshrrev_b32_e32 v2, 4, v1
	v_bitop3_b32 v1, v2, v1, 32 bitop3:0x6c
	v_ashrrev_i32_e32 v0, 31, v252
	v_ashrrev_i32_e32 v3, 31, v1
	v_lshrrev_b32_e32 v0, 26, v0
	v_lshrrev_b32_e32 v3, 26, v3
	v_add_u32_e32 v0, v252, v0
	v_add_u32_e32 v3, v1, v3
	v_ashrrev_i32_e32 v0, 6, v0
	v_lshrrev_b32_e32 v4, 6, v3
	v_and_b32_e32 v3, 0xc0, v3
	v_lshlrev_b32_e32 v2, 3, v0
	v_lshlrev_b32_e32 v0, 5, v0
	v_sub_u32_e32 v1, v1, v3
	v_mov_b32_e32 v3, 1
	v_and_b32_e32 v2, 0x1ffff0, v2
	v_and_b32_e32 v0, 32, v0
	v_ashrrev_i16_sdwa v1, v3, sext(v1) dst_sel:DWORD dst_unused:UNUSED_PAD src0_sel:DWORD src1_sel:BYTE_0
	v_add_u32_sdwa v0, v0, sext(v1) dst_sel:DWORD dst_unused:UNUSED_PAD src0_sel:DWORD src1_sel:WORD_0
	v_add_lshl_u32 v1, v4, v2, 12
	v_add_u32_e32 v140, 0x2000, v138
	v_lshl_add_u32 v139, v0, 1, v1
	v_ashrrev_i32_e32 v0, 31, v140
	v_lshrrev_b32_e32 v0, 22, v0
	v_add_u32_e32 v0, v140, v0
	v_ashrrev_i32_e32 v0, 10, v0
	v_mul_i32_i24_e32 v1, 0x400, v0
	v_sub_u32_e32 v1, v140, v1
	v_lshrrev_b32_e32 v2, 4, v1
	v_bitop3_b32 v1, v2, v1, 32 bitop3:0x6c
	v_ashrrev_i32_e32 v4, 31, v1
	v_lshrrev_b32_e32 v4, 26, v4
	v_add_u32_e32 v4, v1, v4
	v_lshrrev_b32_e32 v5, 6, v4
	v_and_b32_e32 v4, 0xc0, v4
	v_lshlrev_b32_e32 v2, 3, v0
	v_lshlrev_b32_e32 v0, 5, v0
	v_sub_u32_e32 v1, v1, v4
	s_add_u32 s12, s8, 0x2242000
	v_and_b32_e32 v2, 0x1ffff0, v2
	v_and_b32_e32 v0, 32, v0
	v_ashrrev_i16_sdwa v1, v3, sext(v1) dst_sel:DWORD dst_unused:UNUSED_PAD src0_sel:DWORD src1_sel:BYTE_0
	s_addc_u32 s0, s22, 0
	v_add_u32_sdwa v0, v0, sext(v1) dst_sel:DWORD dst_unused:UNUSED_PAD src0_sel:DWORD src1_sel:WORD_0
	v_add_lshl_u32 v1, v5, v2, 12
	s_and_b32 s13, s0, 0xffff
	s_and_b32 s9, s22, 0xffff
	v_lshl_add_u32 v141, v0, 1, v1
	v_and_b32_e32 v0, 15, v195
	v_bfe_u32 v1, v252, 4, 2
	s_and_b32 s3, s2, 3
	s_ashr_i32 s4, s2, 2
	s_cmp_eq_u32 s4, 1
	v_lshlrev_b32_e32 v2, 4, v1
	v_lshlrev_b32_e32 v3, 6, v0
	v_lshlrev_b32_e32 v5, 2, v195
	s_cselect_b64 s[0:1], -1, 0
	s_lshl_b32 s5, s3, 12
	v_or_b32_e32 v4, v2, v3
	v_and_b32_e32 v5, 32, v5
	s_mov_b32 s6, 0x10000
	v_bitop3_b32 v6, v4, s6, v5 bitop3:0xde
	s_mov_b32 s6, 0x14000
	s_cmp_lt_u32 s2, 4
	v_bitop3_b32 v7, v4, s6, v5 bitop3:0xde
	s_mov_b32 s6, 0x18000
	s_cselect_b64 s[16:17], -1, 0
	s_lshl_b32 s24, s3, 5
	v_bitop3_b32 v8, v4, s6, v5 bitop3:0xde
	s_mov_b32 s6, 0x1c000
	v_lshlrev_b32_e32 v1, 2, v1
	s_lshl_b32 s2, s4, 13
	s_or_b32 s25, s24, 0x80
	v_bitop3_b32 v4, v4, s6, v5 bitop3:0xde
	v_lshl_or_b32 v142, s4, 6, v1
	s_or_b32 s4, s2, 0x800
	s_or_b32 s6, s2, 0x1000
	s_or_b32 s7, s2, 0x1800
	v_lshl_or_b32 v144, s3, 4, v0
	s_lshr_b32 s3, s25, 1
	v_lshlrev_b32_e32 v10, 6, v195
	s_add_u32 s18, s8, 0x4442000
	v_lshrrev_b32_e32 v9, 2, v252
	v_and_b32_e32 v10, 0x3c0, v10
	s_addc_u32 s19, s22, 0
	s_mov_b32 s15, 0x20000
	v_bitop3_b32 v3, v2, v5, v3 bitop3:0x36
	v_or_b32_e32 v143, s24, v0
	v_and_b32_e32 v9, 4, v9
	v_bitop3_b32 v2, v10, v5, v2 bitop3:0x36
	v_mov_b32_e32 v145, 0x800
	v_or_b32_e32 v147, s3, v0
	s_add_u32 s20, s8, 0x2040000
	v_cndmask_b32_e64 v0, 0, 1, s[0:1]
	s_mov_b32 s14, 0x2200000
	s_mov_b32 s10, 0xc00000
	s_mov_b32 s11, s15
	v_and_or_b32 v146, v1, 4, v145
	v_or_b32_e32 v148, 0x800, v9
	v_or_b32_e32 v149, 0x801, v9
	v_or_b32_e32 v150, 0x802, v9
	v_or_b32_e32 v151, 0x803, v9
	v_add_u32_e32 v152, 0x10000, v138
	v_add_u32_e32 v153, 0x12000, v138
	v_add_u32_e32 v154, 0x14000, v138
	v_add_u32_e32 v155, 0x16000, v138
	s_movk_i32 s26, 0x4000
	v_add_u32_e32 v156, 0x4000, v138
	v_add_u32_e32 v157, 0x6000, v138
	v_add_u32_e32 v158, 0x18000, v138
	v_add_u32_e32 v159, 0x1a000, v138
	v_add_u32_e32 v160, 0x8000, v138
	v_add_u32_e32 v161, 0xa000, v138
	v_add_u32_e32 v162, 0x1c000, v138
	v_add_u32_e32 v163, 0x1e000, v138
	v_add_u32_e32 v164, 0xc000, v138
	v_add_u32_e32 v165, 0xe000, v138
	s_addc_u32 s21, s22, 0
	s_movk_i32 s27, 0xcd
	v_add_u32_e32 v166, s5, v6
	v_add_u32_e32 v167, s2, v3
	v_add_u32_e32 v168, s4, v2
	v_add_u32_e32 v169, s6, v2
	v_add_u32_e32 v170, s7, v2
	v_add_u32_e32 v171, s5, v7
	v_add_u32_e32 v172, s5, v8
	v_add_u32_e32 v173, s5, v4
	s_movk_i32 s28, 0x3080
	v_mov_b32_e32 v129, 0
	s_movk_i32 s29, 0x7cd
	s_movk_i32 s30, 0x7ce
	s_movk_i32 s31, 0x7cf
	s_movk_i32 s34, 0x7dd
	s_movk_i32 s35, 0x7de
	s_movk_i32 s36, 0x7df
	s_movk_i32 s37, 0x7ed
	s_movk_i32 s38, 0x7ee
	s_movk_i32 s39, 0x7ef
	s_movk_i32 s40, 0x7fd
	s_movk_i32 s41, 0x7fe
; #define WAIT_V(n) asm volatile("s_waitcnt vmcnt(" #n ")" ::: "memory")
; #define BAR __builtin_amdgcn_s_barrier()
;     ...
;     if (NH > 0) {
;       for (int idx = tid; idx < BM * NH; idx += NTHR) {
;         int row = idx / NH, h = idx % NH;
;         const float* pp = parts + (size_t)(m0 + row) * 64 + h * (64 / NH);
;         float s = 0.f;
; #pragma unroll
;         for (int q = 0; q < 64 / NH; ++q) s += pp[q];
;         rstdS[idx] = rsqrtf(s / (float)(K / NH) + 1e-6f);
;       }
;     }
; template <int EPI>
; __device__ void gemm8_phase(const Params& p, const u16* __restrict__ A, const u16* __restrict__ Bt, const int K, const int nN,
;                             unsigned char* smem, const int rep) {
;     ...
;     STAGE(SB(0, 0), Bt, bcol, 0); STAGE(SA(0, 0), A, brow, 0);
;     STAGE(SB(0, 1), Bt, bcol + HALF, 0); STAGE(SA(0, 1), A, brow + HALF, 0);
;     if (wr == 1) BAR;
;     WAIT_V(4); BAR;
	s_movk_i32 s42, 0x7ff
	v_cmp_ne_u32_e64 s[2:3], 1, v0
	s_mov_b32 s43, s78
	s_add_u32 s8, s84, 0x1c40000
	s_addc_u32 s0, s85, 0
	s_and_b32 s9, s0, 0xffff
	s_mov_b32 s10, 0x400000
	s_add_u32 s12, s84, 0x11262000
	s_addc_u32 s0, s85, 0
	s_and_b32 s13, s0, 0xffff
	s_mov_b32 s14, 0x4400000
	s_add_u32 s18, s84, 0x15662000
	s_addc_u32 s19, s85, 0
	s_and_b32 s0, s78, 7
	s_lshr_b32 s1, s78, 3
	s_lshl_b32 s4, s0, 3
	s_lshr_b32 s0, s1, 2
	s_add_i32 s4, s4, s0
	s_and_b32 s1, s1, 3
	s_lshl_b32 s5, s4, 20
	s_lshl_b32 s6, s1, 20
	s_mov_b32 s7, s5
	v_writelane_b32 v255, s4, 51
	v_writelane_b32 v255, s1, 52
	v_mov_b32_e32 v200, v252
	v_lshrrev_b32_e32 v201, 3, v200
	v_and_b32_e32 v202, 7, v200
	v_lshl_add_u32 v201, s4, 8, v201
	v_lshlrev_b32_e32 v201, 8, v201
	v_lshl_add_u32 v203, v202, 5, v201
	global_load_dwordx4 v[208:211], v203, s[18:19]
	global_load_dwordx4 v[212:215], v203, s[18:19] offset:16
	v_add_u32_e32 v200, 512, v252
	v_lshrrev_b32_e32 v201, 3, v200
	v_and_b32_e32 v202, 7, v200
	v_lshl_add_u32 v201, s4, 8, v201
	v_lshlrev_b32_e32 v201, 8, v201
	v_lshl_add_u32 v204, v202, 5, v201
	global_load_dwordx4 v[216:219], v204, s[18:19]
	global_load_dwordx4 v[220:223], v204, s[18:19] offset:16
	v_add_u32_e32 v200, 1024, v252
	v_lshrrev_b32_e32 v201, 3, v200
	v_and_b32_e32 v202, 7, v200
	v_lshl_add_u32 v201, s4, 8, v201
	v_lshlrev_b32_e32 v201, 8, v201
	v_lshl_add_u32 v205, v202, 5, v201
	global_load_dwordx4 v[224:227], v205, s[18:19]
	global_load_dwordx4 v[228:231], v205, s[18:19] offset:16
	v_add_u32_e32 v200, 1536, v252
	v_lshrrev_b32_e32 v201, 3, v200
	v_and_b32_e32 v202, 7, v200
	v_lshl_add_u32 v201, s4, 8, v201
	v_lshlrev_b32_e32 v201, 8, v201
	v_lshl_add_u32 v206, v202, 5, v201
	global_load_dwordx4 v[232:235], v206, s[18:19]
	global_load_dwordx4 v[236:239], v206, s[18:19] offset:16
	v_readfirstlane_b32 s44, v152
	s_nop 1
	s_mov_b32 m0, s44
	s_nop 0
	buffer_load_dwordx4 v139, s[8:11], s6 offen lds
	v_readfirstlane_b32 s44, v153
	s_nop 1
	s_mov_b32 m0, s44
	s_nop 0
	buffer_load_dwordx4 v141, s[8:11], s6 offen lds
	v_readfirstlane_b32 s44, v138
	s_nop 1
	s_mov_b32 m0, s44
	s_nop 0
	buffer_load_dwordx4 v139, s[12:15], s5 offen lds
	v_readfirstlane_b32 s44, v140
	s_nop 1
	s_mov_b32 m0, s44
	s_nop 0
	buffer_load_dwordx4 v141, s[12:15], s5 offen lds
	s_or_b32 s45, s6, 0x80000
	v_readfirstlane_b32 s44, v154
	s_nop 1
	s_mov_b32 m0, s44
	s_nop 0
	buffer_load_dwordx4 v139, s[8:11], s45 offen lds
	v_readfirstlane_b32 s44, v155
	s_nop 1
	s_mov_b32 m0, s44
	s_nop 0
	buffer_load_dwordx4 v141, s[8:11], s45 offen lds
	s_or_b32 s45, s5, 0x80000
	v_readfirstlane_b32 s44, v156
	s_nop 1
	s_mov_b32 m0, s44
	s_nop 0
	buffer_load_dwordx4 v139, s[12:15], s45 offen lds
	v_readfirstlane_b32 s44, v157
	s_nop 1
	s_mov_b32 m0, s44
	s_nop 0
	buffer_load_dwordx4 v141, s[12:15], s45 offen lds
	s_waitcnt vmcnt(8)
	v_add_f32_e32 v200, 0, v208
	v_add_f32_e32 v200, v200, v209
	v_add_f32_e32 v200, v200, v210
	v_add_f32_e32 v200, v200, v211
	v_add_f32_e32 v200, v200, v212
	v_add_f32_e32 v200, v200, v213
	v_add_f32_e32 v200, v200, v214
	v_add_f32_e32 v200, v200, v215
	v_mov_b32_e32 v201, 0x358637bd
	v_fmac_f32_e32 v201, 0x3b800000, v200
	v_rsq_f32_e32 v201, v201
	v_lshlrev_b32_e32 v202, 2, v252
	v_add_u32_e32 v202, 0x20000, v202
	ds_write_b32 v202, v201
	v_add_f32_e32 v200, 0, v216
	v_add_f32_e32 v200, v200, v217
	v_add_f32_e32 v200, v200, v218
	v_add_f32_e32 v200, v200, v219
	v_add_f32_e32 v200, v200, v220
	v_add_f32_e32 v200, v200, v221
	v_add_f32_e32 v200, v200, v222
	v_add_f32_e32 v200, v200, v223
	v_mov_b32_e32 v201, 0x358637bd
	v_fmac_f32_e32 v201, 0x3b800000, v200
	v_rsq_f32_e32 v201, v201
	v_lshlrev_b32_e32 v202, 2, v252
	v_add_u32_e32 v202, 0x20800, v202
	ds_write_b32 v202, v201
	v_add_f32_e32 v200, 0, v224
	v_add_f32_e32 v200, v200, v225
	v_add_f32_e32 v200, v200, v226
	v_add_f32_e32 v200, v200, v227
	v_add_f32_e32 v200, v200, v228
	v_add_f32_e32 v200, v200, v229
	v_add_f32_e32 v200, v200, v230
	v_add_f32_e32 v200, v200, v231
	v_mov_b32_e32 v201, 0x358637bd
	v_fmac_f32_e32 v201, 0x3b800000, v200
	v_rsq_f32_e32 v201, v201
	v_lshlrev_b32_e32 v202, 2, v252
	v_add_u32_e32 v202, 0x21000, v202
	ds_write_b32 v202, v201
	v_add_f32_e32 v200, 0, v232
	v_add_f32_e32 v200, v200, v233
	v_add_f32_e32 v200, v200, v234
	v_add_f32_e32 v200, v200, v235
	v_add_f32_e32 v200, v200, v236
	v_add_f32_e32 v200, v200, v237
	v_add_f32_e32 v200, v200, v238
	v_add_f32_e32 v200, v200, v239
	v_mov_b32_e32 v201, 0x358637bd
	v_fmac_f32_e32 v201, 0x3b800000, v200
	v_rsq_f32_e32 v201, v201
	v_lshlrev_b32_e32 v202, 2, v252
	v_add_u32_e32 v202, 0x21800, v202
	ds_write_b32 v202, v201
	v_and_b32_e32 v128, 15, v195
	v_lshrrev_b32_e32 v129, 2, v252
	v_and_b32_e32 v129, 64, v129
	v_add_u32_e32 v128, v128, v129
	v_lshlrev_b32_e32 v128, 5, v128
	v_add_u32_e32 v128, 0x20000, v128
	s_waitcnt lgkmcnt(0)
	s_and_b64 vcc, exec, s[2:3]
	s_cbranch_vccnz .Lq8_201
	s_barrier

; #define WAIT_V(n) asm volatile("s_waitcnt vmcnt(" #n ")" ::: "memory")
; #define WAIT_L(n) asm volatile("s_waitcnt lgkmcnt(" #n ")" ::: "memory")
; #define BAR __builtin_amdgcn_s_barrier()
; #define SCHED __builtin_amdgcn_sched_barrier(0)
; template <int EPI>
; __device__ void gemm8_phase(const Params& p, const u16* __restrict__ A, const u16* __restrict__ Bt, const int K, const int nN,
;                             unsigned char* smem, const int rep) {
;     ...
;     for (int t = 0; t < nt - 2; t += 2) {
;       LDB(B0, 0, 0); SCHED; LDA(At, 0, 0); STAGE(SA(1, 1), A, brow + HALF, t + 1);
;       WAIT_L(8); BAR; WAIT_L(0); MMA(0, 0, At, B0); BAR; SCHED;
;       LDB(B1, 0, 1); STAGE(SB(0, 0), Bt, bcol, t + 2);
;       BAR; WAIT_L(0); MMA(0, 1, At, B1); BAR;
;       LDA(At, 0, 1); STAGE(SA(0, 0), A, brow, t + 2);
;       BAR; WAIT_L(0); MMA(1, 0, At, B0); BAR; SCHED;
;       STAGE(SB(0, 1), Bt, bcol + HALF, t + 2);
;       WAIT_V(6); BAR; MMA(1, 1, At, B1); BAR;
.Lq8_202:
	ds_read_b128 v[130:133], v166
	ds_read_b128 v[174:177], v166 offset:1024
	ds_read_b128 v[178:181], v166 offset:2048
	ds_read_b128 v[182:185], v166 offset:3072
	s_add_i32 s45, s7, s44
	v_readfirstlane_b32 s47, v164
	s_or_b32 s46, s45, 0x80080
	s_mov_b32 m0, s47
	v_readfirstlane_b32 s47, v165
	ds_read_b128 v[186:189], v167
	ds_read_b128 v[190:193], v167 offset:1024
	ds_read_b128 v[196:199], v168
	ds_read_b128 v[200:203], v168 offset:1024
	ds_read_b128 v[204:207], v169
	ds_read_b128 v[208:211], v169 offset:1024
	ds_read_b128 v[212:215], v170
	ds_read_b128 v[216:219], v170 offset:1024
	buffer_load_dwordx4 v139, s[12:15], s46 offen lds
	s_mov_b32 m0, s47
	s_nop 0
	buffer_load_dwordx4 v141, s[12:15], s46 offen lds
	s_waitcnt lgkmcnt(8)
	s_barrier
	s_waitcnt lgkmcnt(0)
	s_setprio 1
	s_waitcnt lgkmcnt(7)
	v_mfma_f32_16x16x32_bf16 v[124:127], v[130:133], v[186:189], v[124:127]
	v_mfma_f32_16x16x32_bf16 v[120:123], v[178:181], v[186:189], v[120:123]
	s_waitcnt lgkmcnt(5)
	v_mfma_f32_16x16x32_bf16 v[116:119], v[130:133], v[196:199], v[116:119]
	v_mfma_f32_16x16x32_bf16 v[112:115], v[178:181], v[196:199], v[112:115]
	s_waitcnt lgkmcnt(3)
	v_mfma_f32_16x16x32_bf16 v[108:111], v[130:133], v[204:207], v[108:111]
	v_mfma_f32_16x16x32_bf16 v[104:107], v[178:181], v[204:207], v[104:107]
	s_waitcnt lgkmcnt(1)
	v_mfma_f32_16x16x32_bf16 v[100:103], v[130:133], v[212:215], v[100:103]
	v_mfma_f32_16x16x32_bf16 v[96:99], v[178:181], v[212:215], v[96:99]
	v_mfma_f32_16x16x32_bf16 v[124:127], v[174:177], v[190:193], v[124:127]
	v_mfma_f32_16x16x32_bf16 v[120:123], v[182:185], v[190:193], v[120:123]
	v_mfma_f32_16x16x32_bf16 v[116:119], v[174:177], v[200:203], v[116:119]
	v_mfma_f32_16x16x32_bf16 v[112:115], v[182:185], v[200:203], v[112:115]
	v_mfma_f32_16x16x32_bf16 v[108:111], v[174:177], v[208:211], v[108:111]
	v_mfma_f32_16x16x32_bf16 v[104:107], v[182:185], v[208:211], v[104:107]
	s_waitcnt lgkmcnt(0)
	v_mfma_f32_16x16x32_bf16 v[100:103], v[174:177], v[216:219], v[100:103]
	v_mfma_f32_16x16x32_bf16 v[96:99], v[182:185], v[216:219], v[96:99]
	s_setprio 0
	s_barrier
	s_add_i32 s46, s6, s44
	v_readfirstlane_b32 s48, v152
	s_add_i32 s47, s46, 0x100
	s_mov_b32 m0, s48
	v_readfirstlane_b32 s48, v153
	ds_read_b128 v[220:223], v171
	ds_read_b128 v[224:227], v171 offset:1024
	ds_read_b128 v[228:231], v171 offset:2048
	ds_read_b128 v[232:235], v171 offset:3072
	buffer_load_dwordx4 v139, s[8:11], s47 offen lds
	s_mov_b32 m0, s48
	s_nop 0
	buffer_load_dwordx4 v141, s[8:11], s47 offen lds
	s_barrier
	s_waitcnt lgkmcnt(0)
	s_setprio 1
	s_waitcnt lgkmcnt(3)
	v_mfma_f32_16x16x32_bf16 v[92:95], v[220:223], v[186:189], v[92:95]
	s_waitcnt lgkmcnt(1)
	v_mfma_f32_16x16x32_bf16 v[88:91], v[228:231], v[186:189], v[88:91]
	v_mfma_f32_16x16x32_bf16 v[84:87], v[220:223], v[196:199], v[84:87]
	v_mfma_f32_16x16x32_bf16 v[80:83], v[228:231], v[196:199], v[80:83]
	v_mfma_f32_16x16x32_bf16 v[76:79], v[220:223], v[204:207], v[76:79]
	v_mfma_f32_16x16x32_bf16 v[72:75], v[228:231], v[204:207], v[72:75]
	v_mfma_f32_16x16x32_bf16 v[68:71], v[220:223], v[212:215], v[68:71]
	v_mfma_f32_16x16x32_bf16 v[64:67], v[228:231], v[212:215], v[64:67]
	v_mfma_f32_16x16x32_bf16 v[92:95], v[224:227], v[190:193], v[92:95]
	s_waitcnt lgkmcnt(0)
	v_mfma_f32_16x16x32_bf16 v[88:91], v[232:235], v[190:193], v[88:91]
	v_mfma_f32_16x16x32_bf16 v[84:87], v[224:227], v[200:203], v[84:87]
	v_mfma_f32_16x16x32_bf16 v[80:83], v[232:235], v[200:203], v[80:83]
	v_mfma_f32_16x16x32_bf16 v[76:79], v[224:227], v[208:211], v[76:79]
	v_mfma_f32_16x16x32_bf16 v[72:75], v[232:235], v[208:211], v[72:75]
	v_mfma_f32_16x16x32_bf16 v[68:71], v[224:227], v[216:219], v[68:71]
	v_mfma_f32_16x16x32_bf16 v[64:67], v[232:235], v[216:219], v[64:67]
	s_setprio 0
	v_readfirstlane_b32 s48, v138
	s_add_i32 s47, s45, 0x100
	s_mov_b32 m0, s48
	v_readfirstlane_b32 s48, v140
	s_barrier
	ds_read_b128 v[186:189], v167 offset:16384
	ds_read_b128 v[190:193], v167 offset:17408
	ds_read_b128 v[196:199], v168 offset:16384
	ds_read_b128 v[200:203], v168 offset:17408
	ds_read_b128 v[204:207], v169 offset:16384
	ds_read_b128 v[208:211], v169 offset:17408
	ds_read_b128 v[212:215], v170 offset:16384
	ds_read_b128 v[216:219], v170 offset:17408
	buffer_load_dwordx4 v139, s[12:15], s47 offen lds
	s_mov_b32 m0, s48
	s_nop 0
	buffer_load_dwordx4 v141, s[12:15], s47 offen lds
	s_barrier
	s_waitcnt lgkmcnt(0)
	s_setprio 1
	s_waitcnt lgkmcnt(7)
	v_mfma_f32_16x16x32_bf16 v[60:63], v[130:133], v[186:189], v[60:63]
	v_mfma_f32_16x16x32_bf16 v[56:59], v[178:181], v[186:189], v[56:59]
	s_waitcnt lgkmcnt(5)
	v_mfma_f32_16x16x32_bf16 v[52:55], v[130:133], v[196:199], v[52:55]
	v_mfma_f32_16x16x32_bf16 v[48:51], v[178:181], v[196:199], v[48:51]
	s_waitcnt lgkmcnt(3)
	v_mfma_f32_16x16x32_bf16 v[44:47], v[130:133], v[204:207], v[44:47]
	v_mfma_f32_16x16x32_bf16 v[40:43], v[178:181], v[204:207], v[40:43]
	s_waitcnt lgkmcnt(1)
	v_mfma_f32_16x16x32_bf16 v[36:39], v[130:133], v[212:215], v[36:39]
	v_mfma_f32_16x16x32_bf16 v[32:35], v[178:181], v[212:215], v[32:35]
	v_mfma_f32_16x16x32_bf16 v[60:63], v[174:177], v[190:193], v[60:63]
	v_mfma_f32_16x16x32_bf16 v[56:59], v[182:185], v[190:193], v[56:59]
	v_mfma_f32_16x16x32_bf16 v[52:55], v[174:177], v[200:203], v[52:55]
	v_mfma_f32_16x16x32_bf16 v[48:51], v[182:185], v[200:203], v[48:51]
	v_mfma_f32_16x16x32_bf16 v[44:47], v[174:177], v[208:211], v[44:47]
	v_mfma_f32_16x16x32_bf16 v[40:43], v[182:185], v[208:211], v[40:43]
	s_waitcnt lgkmcnt(0)
	v_mfma_f32_16x16x32_bf16 v[36:39], v[174:177], v[216:219], v[36:39]
	v_mfma_f32_16x16x32_bf16 v[32:35], v[182:185], v[216:219], v[32:35]
	s_setprio 0
	s_barrier
; #define WAIT_V(n) asm volatile("s_waitcnt vmcnt(" #n ")" ::: "memory")
; #define WAIT_L(n) asm volatile("s_waitcnt lgkmcnt(" #n ")" ::: "memory")
; #define BAR __builtin_amdgcn_s_barrier()
; #define SCHED __builtin_amdgcn_sched_barrier(0)
; template <int EPI>
; __device__ void gemm8_phase(const Params& p, const u16* __restrict__ A, const u16* __restrict__ Bt, const int K, const int nN,
;                             unsigned char* smem, const int rep) {
;     ...
;       STAGE(SB(0, 1), Bt, bcol + HALF, t + 2);
;       WAIT_V(6); BAR; MMA(1, 1, At, B1); BAR;
;       LDB(B0, 1, 0); SCHED; LDA(At, 1, 0); STAGE(SA(0, 1), A, brow + HALF, t + 2);
;       WAIT_L(8); BAR; WAIT_L(0); MMA(0, 0, At, B0); BAR; SCHED;
;       LDB(B1, 1, 1); STAGE(SB(1, 0), Bt, bcol, t + 3);
;       BAR; WAIT_L(0); MMA(0, 1, At, B1); BAR;
;       LDA(At, 1, 1); STAGE(SA(1, 0), A, brow, t + 3);
;       BAR; WAIT_L(0); MMA(1, 0, At, B0); BAR; SCHED;
	v_readfirstlane_b32 s48, v154
	s_add_i32 s47, s46, 0x80100
	s_mov_b32 m0, s48
	v_readfirstlane_b32 s48, v155
	buffer_load_dwordx4 v139, s[8:11], s47 offen lds
	s_mov_b32 m0, s48
	s_nop 0
	buffer_load_dwordx4 v141, s[8:11], s47 offen lds
	s_waitcnt vmcnt(6)
	s_barrier
	s_setprio 1
	v_mfma_f32_16x16x32_bf16 v[28:31], v[220:223], v[186:189], v[28:31]
	v_mfma_f32_16x16x32_bf16 v[24:27], v[228:231], v[186:189], v[24:27]
	v_mfma_f32_16x16x32_bf16 v[20:23], v[220:223], v[196:199], v[20:23]
	v_mfma_f32_16x16x32_bf16 v[16:19], v[228:231], v[196:199], v[16:19]
	v_mfma_f32_16x16x32_bf16 v[12:15], v[220:223], v[204:207], v[12:15]
	v_mfma_f32_16x16x32_bf16 v[8:11], v[228:231], v[204:207], v[8:11]
	v_mfma_f32_16x16x32_bf16 v[4:7], v[220:223], v[212:215], v[4:7]
	v_mfma_f32_16x16x32_bf16 v[0:3], v[228:231], v[212:215], v[0:3]
	v_mfma_f32_16x16x32_bf16 v[28:31], v[224:227], v[190:193], v[28:31]
	v_mfma_f32_16x16x32_bf16 v[24:27], v[232:235], v[190:193], v[24:27]
	v_mfma_f32_16x16x32_bf16 v[20:23], v[224:227], v[200:203], v[20:23]
	v_mfma_f32_16x16x32_bf16 v[16:19], v[232:235], v[200:203], v[16:19]
	v_mfma_f32_16x16x32_bf16 v[12:15], v[224:227], v[208:211], v[12:15]
	v_mfma_f32_16x16x32_bf16 v[8:11], v[232:235], v[208:211], v[8:11]
	v_mfma_f32_16x16x32_bf16 v[4:7], v[224:227], v[216:219], v[4:7]
	v_mfma_f32_16x16x32_bf16 v[0:3], v[232:235], v[216:219], v[0:3]
	s_setprio 0
	s_barrier
	ds_read_b128 v[130:133], v172
	ds_read_b128 v[174:177], v172 offset:1024
	ds_read_b128 v[178:181], v172 offset:2048
	ds_read_b128 v[182:185], v172 offset:3072
	v_readfirstlane_b32 s48, v156
	s_add_i32 s47, s45, 0x80100
	s_mov_b32 m0, s48
	v_readfirstlane_b32 s48, v157
	ds_read_b128 v[186:189], v167 offset:32768
	ds_read_b128 v[190:193], v167 offset:33792
	ds_read_b128 v[196:199], v168 offset:32768
	ds_read_b128 v[200:203], v168 offset:33792
	ds_read_b128 v[204:207], v169 offset:32768
	ds_read_b128 v[208:211], v169 offset:33792
	ds_read_b128 v[212:215], v170 offset:32768
	ds_read_b128 v[216:219], v170 offset:33792
	buffer_load_dwordx4 v139, s[12:15], s47 offen lds
	s_mov_b32 m0, s48
	s_nop 0
	buffer_load_dwordx4 v141, s[12:15], s47 offen lds
	s_waitcnt lgkmcnt(8)
	s_barrier
	s_waitcnt lgkmcnt(0)
	s_setprio 1
	s_waitcnt lgkmcnt(7)
	v_mfma_f32_16x16x32_bf16 v[124:127], v[130:133], v[186:189], v[124:127]
	v_mfma_f32_16x16x32_bf16 v[120:123], v[178:181], v[186:189], v[120:123]
	s_waitcnt lgkmcnt(5)
	v_mfma_f32_16x16x32_bf16 v[116:119], v[130:133], v[196:199], v[116:119]
	v_mfma_f32_16x16x32_bf16 v[112:115], v[178:181], v[196:199], v[112:115]
	s_waitcnt lgkmcnt(3)
	v_mfma_f32_16x16x32_bf16 v[108:111], v[130:133], v[204:207], v[108:111]
	v_mfma_f32_16x16x32_bf16 v[104:107], v[178:181], v[204:207], v[104:107]
	s_waitcnt lgkmcnt(1)
	v_mfma_f32_16x16x32_bf16 v[100:103], v[130:133], v[212:215], v[100:103]
	v_mfma_f32_16x16x32_bf16 v[96:99], v[178:181], v[212:215], v[96:99]
	v_mfma_f32_16x16x32_bf16 v[124:127], v[174:177], v[190:193], v[124:127]
	v_mfma_f32_16x16x32_bf16 v[120:123], v[182:185], v[190:193], v[120:123]
	v_mfma_f32_16x16x32_bf16 v[116:119], v[174:177], v[200:203], v[116:119]
	v_mfma_f32_16x16x32_bf16 v[112:115], v[182:185], v[200:203], v[112:115]
	v_mfma_f32_16x16x32_bf16 v[108:111], v[174:177], v[208:211], v[108:111]
	v_mfma_f32_16x16x32_bf16 v[104:107], v[182:185], v[208:211], v[104:107]
	s_waitcnt lgkmcnt(0)
	v_mfma_f32_16x16x32_bf16 v[100:103], v[174:177], v[216:219], v[100:103]
	v_mfma_f32_16x16x32_bf16 v[96:99], v[182:185], v[216:219], v[96:99]
	s_setprio 0
	s_barrier
	v_readfirstlane_b32 s48, v158
	s_add_i32 s47, s46, 0x180
	s_mov_b32 m0, s48
	v_readfirstlane_b32 s48, v159
	ds_read_b128 v[220:223], v173
	ds_read_b128 v[224:227], v173 offset:1024
	ds_read_b128 v[228:231], v173 offset:2048
	ds_read_b128 v[232:235], v173 offset:3072
	buffer_load_dwordx4 v139, s[8:11], s47 offen lds
	s_mov_b32 m0, s48
	s_nop 0
	buffer_load_dwordx4 v141, s[8:11], s47 offen lds
	s_barrier
	s_waitcnt lgkmcnt(0)
	s_setprio 1
	s_waitcnt lgkmcnt(3)
	v_mfma_f32_16x16x32_bf16 v[92:95], v[220:223], v[186:189], v[92:95]
	s_waitcnt lgkmcnt(1)
	v_mfma_f32_16x16x32_bf16 v[88:91], v[228:231], v[186:189], v[88:91]
	v_mfma_f32_16x16x32_bf16 v[84:87], v[220:223], v[196:199], v[84:87]
	v_mfma_f32_16x16x32_bf16 v[80:83], v[228:231], v[196:199], v[80:83]
	v_mfma_f32_16x16x32_bf16 v[76:79], v[220:223], v[204:207], v[76:79]
	v_mfma_f32_16x16x32_bf16 v[72:75], v[228:231], v[204:207], v[72:75]
	v_mfma_f32_16x16x32_bf16 v[68:71], v[220:223], v[212:215], v[68:71]
	v_mfma_f32_16x16x32_bf16 v[64:67], v[228:231], v[212:215], v[64:67]
	v_mfma_f32_16x16x32_bf16 v[92:95], v[224:227], v[190:193], v[92:95]
	s_waitcnt lgkmcnt(0)
	v_mfma_f32_16x16x32_bf16 v[88:91], v[232:235], v[190:193], v[88:91]
	v_mfma_f32_16x16x32_bf16 v[84:87], v[224:227], v[200:203], v[84:87]
	v_mfma_f32_16x16x32_bf16 v[80:83], v[232:235], v[200:203], v[80:83]
	v_mfma_f32_16x16x32_bf16 v[76:79], v[224:227], v[208:211], v[76:79]
	v_mfma_f32_16x16x32_bf16 v[72:75], v[232:235], v[208:211], v[72:75]
	v_mfma_f32_16x16x32_bf16 v[68:71], v[224:227], v[216:219], v[68:71]
	v_mfma_f32_16x16x32_bf16 v[64:67], v[232:235], v[216:219], v[64:67]
	s_setprio 0
	v_readfirstlane_b32 s47, v160
	s_addk_i32 s45, 0x180
	s_mov_b32 m0, s47
	v_readfirstlane_b32 s47, v161
	s_barrier
	ds_read_b128 v[186:189], v167 offset:49152
	ds_read_b128 v[190:193], v167 offset:50176
	ds_read_b128 v[196:199], v168 offset:49152
	ds_read_b128 v[200:203], v168 offset:50176
	ds_read_b128 v[204:207], v169 offset:49152
	ds_read_b128 v[208:211], v169 offset:50176
	ds_read_b128 v[212:215], v170 offset:49152
	ds_read_b128 v[216:219], v170 offset:50176
	buffer_load_dwordx4 v139, s[12:15], s45 offen lds
	s_mov_b32 m0, s47
	s_nop 0
	buffer_load_dwordx4 v141, s[12:15], s45 offen lds
	s_barrier
; #define WAIT_V(n) asm volatile("s_waitcnt vmcnt(" #n ")" ::: "memory")
; #define WAIT_L(n) asm volatile("s_waitcnt lgkmcnt(" #n ")" ::: "memory")
; #define BAR __builtin_amdgcn_s_barrier()
; #define SCHED __builtin_amdgcn_sched_barrier(0)
;     ...
;       if (NH > 0) {
;         const int per = KT / NH;
;         if (((kt + 1) % per) == 0) {
;           const int h = (kt + 1) / per - 1;
; template <int EPI>
; __device__ void gemm8_phase(const Params& p, const u16* __restrict__ A, const u16* __restrict__ Bt, const int K, const int nN,
;                             unsigned char* smem, const int rep) {
;     ...
;       BAR; WAIT_L(0); MMA(1, 0, At, B0); BAR; SCHED;
;       STAGE(SB(1, 1), Bt, bcol + HALF, t + 3);
;       WAIT_V(6); BAR; MMA(1, 1, At, B1); BAR;
	s_waitcnt lgkmcnt(0)
	s_setprio 1
	s_waitcnt lgkmcnt(7)
	v_mfma_f32_16x16x32_bf16 v[60:63], v[130:133], v[186:189], v[60:63]
	v_mfma_f32_16x16x32_bf16 v[56:59], v[178:181], v[186:189], v[56:59]
	s_waitcnt lgkmcnt(5)
	v_mfma_f32_16x16x32_bf16 v[52:55], v[130:133], v[196:199], v[52:55]
	v_mfma_f32_16x16x32_bf16 v[48:51], v[178:181], v[196:199], v[48:51]
	s_waitcnt lgkmcnt(3)
	v_mfma_f32_16x16x32_bf16 v[44:47], v[130:133], v[204:207], v[44:47]
	v_mfma_f32_16x16x32_bf16 v[40:43], v[178:181], v[204:207], v[40:43]
	s_waitcnt lgkmcnt(1)
	v_mfma_f32_16x16x32_bf16 v[36:39], v[130:133], v[212:215], v[36:39]
	v_mfma_f32_16x16x32_bf16 v[32:35], v[178:181], v[212:215], v[32:35]
	v_mfma_f32_16x16x32_bf16 v[60:63], v[174:177], v[190:193], v[60:63]
	v_mfma_f32_16x16x32_bf16 v[56:59], v[182:185], v[190:193], v[56:59]
	v_mfma_f32_16x16x32_bf16 v[52:55], v[174:177], v[200:203], v[52:55]
	v_mfma_f32_16x16x32_bf16 v[48:51], v[182:185], v[200:203], v[48:51]
	v_mfma_f32_16x16x32_bf16 v[44:47], v[174:177], v[208:211], v[44:47]
	v_mfma_f32_16x16x32_bf16 v[40:43], v[182:185], v[208:211], v[40:43]
	s_waitcnt lgkmcnt(0)
	v_mfma_f32_16x16x32_bf16 v[36:39], v[174:177], v[216:219], v[36:39]
	v_mfma_f32_16x16x32_bf16 v[32:35], v[182:185], v[216:219], v[32:35]
	s_setprio 0
	s_barrier
	v_readfirstlane_b32 s45, v162
	s_add_i32 s46, s46, 0x80180
	s_mov_b32 m0, s45
	v_readfirstlane_b32 s45, v163
	buffer_load_dwordx4 v139, s[8:11], s46 offen lds
	s_mov_b32 m0, s45
	s_nop 0
	buffer_load_dwordx4 v141, s[8:11], s46 offen lds
	s_waitcnt vmcnt(6)
	s_barrier
	s_setprio 1
	v_mfma_f32_16x16x32_bf16 v[28:31], v[220:223], v[186:189], v[28:31]
	v_mfma_f32_16x16x32_bf16 v[24:27], v[228:231], v[186:189], v[24:27]
	v_mfma_f32_16x16x32_bf16 v[20:23], v[220:223], v[196:199], v[20:23]
	v_mfma_f32_16x16x32_bf16 v[16:19], v[228:231], v[196:199], v[16:19]
	v_mfma_f32_16x16x32_bf16 v[12:15], v[220:223], v[204:207], v[12:15]
	v_mfma_f32_16x16x32_bf16 v[8:11], v[228:231], v[204:207], v[8:11]
	v_mfma_f32_16x16x32_bf16 v[4:7], v[220:223], v[212:215], v[4:7]
	v_mfma_f32_16x16x32_bf16 v[0:3], v[228:231], v[212:215], v[0:3]
	v_mfma_f32_16x16x32_bf16 v[28:31], v[224:227], v[190:193], v[28:31]
	v_mfma_f32_16x16x32_bf16 v[24:27], v[232:235], v[190:193], v[24:27]
	v_mfma_f32_16x16x32_bf16 v[20:23], v[224:227], v[200:203], v[20:23]
	v_mfma_f32_16x16x32_bf16 v[16:19], v[232:235], v[200:203], v[16:19]
	v_mfma_f32_16x16x32_bf16 v[12:15], v[224:227], v[208:211], v[12:15]
	v_mfma_f32_16x16x32_bf16 v[8:11], v[232:235], v[208:211], v[8:11]
	v_mfma_f32_16x16x32_bf16 v[4:7], v[224:227], v[216:219], v[4:7]
	v_mfma_f32_16x16x32_bf16 v[0:3], v[232:235], v[216:219], v[0:3]
	s_setprio 0
	s_add_i32 s48, s33, 4
	s_and_b32 s48, s48, 3
	s_cmp_lg_u32 s48, 0
	s_cbranch_scc1 .Lq8_nosc
;     ...
;       if (NH > 0) {
;         const int per = KT / NH;
;         if (((kt + 1) % per) == 0) {
;           const int h = (kt + 1) / per - 1;
; #pragma unroll
;           for (int mf = 0; mf < 4; ++mf)
; #pragma unroll
;             for (int r = 0; r < 4; ++r) {
;               float s = rstdS[(wm * 64 + mf * 16 + 4 * g + r) * NH + h];
; #pragma unroll
;               for (int nf = 0; nf < 4; ++nf) {
;                 accT[mf][nf][r] += s * acc[mf][nf][r];
;                 acc[mf][nf][r] = 0.f;
;               }
;             }
;         }
	s_add_i32 s48, s33, 4
	s_lshr_b32 s48, s48, 2
	s_sub_i32 s48, s48, 1
	s_lshl_b32 s48, s48, 2
	v_add_u32_e32 v220, s48, v128
	ds_read_b32 v221, v220
	ds_read_b32 v222, v220 offset:4
	ds_read_b32 v223, v220 offset:512
	ds_read_b32 v224, v220 offset:516
	ds_read_b32 v225, v220 offset:1024
	ds_read_b32 v226, v220 offset:1028
	ds_read_b32 v227, v220 offset:1536
	ds_read_b32 v228, v220 offset:1540
	ds_read_b32 v229, v220 offset:4096
	ds_read_b32 v230, v220 offset:4100
	ds_read_b32 v231, v220 offset:4608
	ds_read_b32 v232, v220 offset:4612
	ds_read_b32 v233, v220 offset:5120
	ds_read_b32 v234, v220 offset:5124
	ds_read_b32 v235, v220 offset:5632
	ds_read_b32 v236, v220 offset:5636
	s_waitcnt lgkmcnt(0)
	v_rcp_f32_e32 v222, v222
	v_rcp_f32_e32 v224, v224
	v_rcp_f32_e32 v226, v226
	v_rcp_f32_e32 v228, v228
	v_rcp_f32_e32 v230, v230
	v_rcp_f32_e32 v232, v232
	v_rcp_f32_e32 v234, v234
	v_rcp_f32_e32 v236, v236
	s_nop 0
	v_mul_f32_e32 v221, v221, v222
	v_mul_f32_e32 v223, v223, v224
	v_mul_f32_e32 v225, v225, v226
	v_mul_f32_e32 v227, v227, v228
	v_mul_f32_e32 v229, v229, v230
	v_mul_f32_e32 v231, v231, v232
	v_mul_f32_e32 v233, v233, v234
	v_mul_f32_e32 v235, v235, v236
	v_mul_f32_e32 v124, v221, v124
	v_mul_f32_e32 v125, v221, v125
	v_mul_f32_e32 v126, v221, v126
	v_mul_f32_e32 v127, v221, v127
	v_mul_f32_e32 v120, v221, v120
	v_mul_f32_e32 v121, v221, v121
	v_mul_f32_e32 v122, v221, v122
	v_mul_f32_e32 v123, v221, v123
	v_mul_f32_e32 v92, v221, v92
	v_mul_f32_e32 v93, v221, v93
	v_mul_f32_e32 v94, v221, v94
	v_mul_f32_e32 v95, v221, v95
	v_mul_f32_e32 v88, v221, v88
	v_mul_f32_e32 v89, v221, v89
	v_mul_f32_e32 v90, v221, v90
	v_mul_f32_e32 v91, v221, v91
	v_mul_f32_e32 v116, v223, v116
	v_mul_f32_e32 v117, v223, v117
	v_mul_f32_e32 v118, v223, v118
	v_mul_f32_e32 v119, v223, v119
	v_mul_f32_e32 v112, v223, v112
	v_mul_f32_e32 v113, v223, v113
	v_mul_f32_e32 v114, v223, v114
	v_mul_f32_e32 v115, v223, v115
	v_mul_f32_e32 v84, v223, v84
	v_mul_f32_e32 v85, v223, v85
	v_mul_f32_e32 v86, v223, v86
	v_mul_f32_e32 v87, v223, v87
	v_mul_f32_e32 v80, v223, v80
	v_mul_f32_e32 v81, v223, v81
	v_mul_f32_e32 v82, v223, v82
	v_mul_f32_e32 v83, v223, v83
	v_mul_f32_e32 v108, v225, v108
	v_mul_f32_e32 v109, v225, v109
	v_mul_f32_e32 v110, v225, v110
	v_mul_f32_e32 v111, v225, v111
	v_mul_f32_e32 v104, v225, v104
	v_mul_f32_e32 v105, v225, v105
	v_mul_f32_e32 v106, v225, v106
	v_mul_f32_e32 v107, v225, v107
	v_mul_f32_e32 v76, v225, v76
	v_mul_f32_e32 v77, v225, v77
	v_mul_f32_e32 v78, v225, v78
	v_mul_f32_e32 v79, v225, v79
	v_mul_f32_e32 v72, v225, v72
	v_mul_f32_e32 v73, v225, v73
	v_mul_f32_e32 v74, v225, v74
	v_mul_f32_e32 v75, v225, v75
	v_mul_f32_e32 v100, v227, v100
	v_mul_f32_e32 v101, v227, v101
	v_mul_f32_e32 v102, v227, v102
	v_mul_f32_e32 v103, v227, v103
	v_mul_f32_e32 v96, v227, v96
	v_mul_f32_e32 v97, v227, v97
	v_mul_f32_e32 v98, v227, v98
	v_mul_f32_e32 v99, v227, v99
	v_mul_f32_e32 v68, v227, v68
	v_mul_f32_e32 v69, v227, v69
	v_mul_f32_e32 v70, v227, v70
	v_mul_f32_e32 v71, v227, v71
	v_mul_f32_e32 v64, v227, v64
	v_mul_f32_e32 v65, v227, v65
	v_mul_f32_e32 v66, v227, v66
	v_mul_f32_e32 v67, v227, v67
	v_mul_f32_e32 v60, v229, v60
	v_mul_f32_e32 v61, v229, v61
	v_mul_f32_e32 v62, v229, v62
	v_mul_f32_e32 v63, v229, v63
	v_mul_f32_e32 v56, v229, v56
	v_mul_f32_e32 v57, v229, v57
	v_mul_f32_e32 v58, v229, v58
	v_mul_f32_e32 v59, v229, v59
	v_mul_f32_e32 v28, v229, v28
	v_mul_f32_e32 v29, v229, v29
	v_mul_f32_e32 v30, v229, v30
	v_mul_f32_e32 v31, v229, v31
	v_mul_f32_e32 v24, v229, v24
	v_mul_f32_e32 v25, v229, v25
	v_mul_f32_e32 v26, v229, v26
	v_mul_f32_e32 v27, v229, v27
	v_mul_f32_e32 v52, v231, v52
	v_mul_f32_e32 v53, v231, v53
	v_mul_f32_e32 v54, v231, v54
	v_mul_f32_e32 v55, v231, v55
	v_mul_f32_e32 v48, v231, v48
	v_mul_f32_e32 v49, v231, v49
	v_mul_f32_e32 v50, v231, v50
	v_mul_f32_e32 v51, v231, v51
	v_mul_f32_e32 v20, v231, v20
	v_mul_f32_e32 v21, v231, v21
	v_mul_f32_e32 v22, v231, v22
	v_mul_f32_e32 v23, v231, v23
	v_mul_f32_e32 v16, v231, v16
	v_mul_f32_e32 v17, v231, v17
	v_mul_f32_e32 v18, v231, v18
	v_mul_f32_e32 v19, v231, v19
	v_mul_f32_e32 v44, v233, v44
	v_mul_f32_e32 v45, v233, v45
	v_mul_f32_e32 v46, v233, v46
	v_mul_f32_e32 v47, v233, v47
	v_mul_f32_e32 v40, v233, v40
	v_mul_f32_e32 v41, v233, v41
	v_mul_f32_e32 v42, v233, v42
	v_mul_f32_e32 v43, v233, v43
	v_mul_f32_e32 v12, v233, v12
	v_mul_f32_e32 v13, v233, v13
	v_mul_f32_e32 v14, v233, v14
	v_mul_f32_e32 v15, v233, v15
	v_mul_f32_e32 v8, v233, v8
	v_mul_f32_e32 v9, v233, v9
	v_mul_f32_e32 v10, v233, v10
	v_mul_f32_e32 v11, v233, v11
	v_mul_f32_e32 v36, v235, v36
	v_mul_f32_e32 v37, v235, v37
	v_mul_f32_e32 v38, v235, v38
	v_mul_f32_e32 v39, v235, v39
	v_mul_f32_e32 v32, v235, v32
	v_mul_f32_e32 v33, v235, v33
	v_mul_f32_e32 v34, v235, v34
	v_mul_f32_e32 v35, v235, v35
	v_mul_f32_e32 v4, v235, v4
	v_mul_f32_e32 v5, v235, v5
	v_mul_f32_e32 v6, v235, v6
	v_mul_f32_e32 v7, v235, v7
	v_mul_f32_e32 v0, v235, v0
	v_mul_f32_e32 v1, v235, v1
	v_mul_f32_e32 v2, v235, v2
	v_mul_f32_e32 v3, v235, v3

;     ...
;       if (NH > 0) {
;         const int per = KT / NH;
;         if (((kt + 1) % per) == 0) {
;           const int h = (kt + 1) / per - 1;
; #pragma unroll
;           for (int mf = 0; mf < 4; ++mf)
; #pragma unroll
;             for (int r = 0; r < 4; ++r) {
;               float s = rstdS[(wm * 64 + mf * 16 + 4 * g + r) * NH + h];
; #pragma unroll
;               for (int nf = 0; nf < 4; ++nf) {
;                 accT[mf][nf][r] += s * acc[mf][nf][r];
;                 acc[mf][nf][r] = 0.f;
;               }
;             }
;         }
;     ...
;       if (EPI == 1) {
; #pragma unroll
;         for (int r = 0; r < 4; ++r) {
;           const int row = m0 + wm * 64 + mf * 16 + 4 * g + r;
; #pragma unroll
;           for (int nf = 0; nf < 4; ++nf) {
;             const int col = n0 + wn * 64 + nf * 16 + l15;
;             rvv[r][nf] = resid ? resid[(size_t)row * 1024 + col] : xrow(p, row)[col];
;           }
;         }
;       }
; #pragma unroll
;       for (int r = 0; r < 4; ++r) {
;         const int row = m0 + wm * 64 + mf * 16 + 4 * g + r;
;         if (EPI == 0) {
;           u16* proj = (u16*)(p.ws + OFF_PROJ) + (size_t)row * PROJ_LD;
;           if (n0 < 2048) {
;             const float2* rope = (const float2*)(p.ws + OFF_ROPE);
;             const int pi = row < NPROMPT ? (row & 2047) : 2048 + ((row - NPROMPT) & 7);
; #pragma unroll
;             for (int np = 0; np < 2; ++np) {
;               const int pc = n0 + wn * 64 + np * 32;
;               const int i = ((pc & 255) >> 5) * 16 + l15;
;               const float2 cs = rope[pi * 128 + i];
;               const float x1 = acc[mf][2 * np][r], x2 = acc[mf][2 * np + 1][r];
;               float y1 = x1 * cs.x - x2 * cs.y, y2 = x1 * cs.y + x2 * cs.x;
;               if (pc >= 1024) { y1 *= 0.0625f; y2 *= 0.0625f; }
;               const int f1 = (pc & ~255) + i;
;               proj[f1] = f2bf(y1);
;               proj[f1 + 128] = f2bf(y2);
;             }
;           } else {
; #pragma unroll
;             for (int nf = 0; nf < 4; ++nf) proj[n0 + wn * 64 + nf * 16 + l15] = f2bf(acc[mf][nf][r]);
;           }
;         } else if (EPI == 1) {
; #pragma unroll
;           for (int nf = 0; nf < 4; ++nf) {
;             const int col = n0 + wn * 64 + nf * 16 + l15;
;             const float a = (NH > 0) ? accT[mf][nf][r] : acc[mf][nf][r];
;             outf[(size_t)row * 1024 + col] = rvv[r][nf] + a;
.Lq8_205:
	v_add_u32_e32 v220, 28, v128
	ds_read_b32 v221, v220
	ds_read_b32 v223, v220 offset:512
	ds_read_b32 v225, v220 offset:1024
	ds_read_b32 v227, v220 offset:1536
	ds_read_b32 v229, v220 offset:4096
	ds_read_b32 v231, v220 offset:4608
	ds_read_b32 v233, v220 offset:5120
	ds_read_b32 v235, v220 offset:5632
	s_waitcnt lgkmcnt(0)
	s_nop 7
	v_mul_f32_e32 v120, v221, v120
	v_mul_f32_e32 v121, v221, v121
	v_mul_f32_e32 v122, v221, v122
	v_mul_f32_e32 v123, v221, v123
	v_mul_f32_e32 v124, v221, v124
	v_mul_f32_e32 v125, v221, v125
	v_mul_f32_e32 v126, v221, v126
	v_mul_f32_e32 v127, v221, v127
	v_mul_f32_e32 v112, v221, v112
	v_mul_f32_e32 v113, v221, v113
	v_mul_f32_e32 v114, v221, v114
	v_mul_f32_e32 v115, v221, v115
	v_mul_f32_e32 v116, v221, v116
	v_mul_f32_e32 v117, v221, v117
	v_mul_f32_e32 v118, v221, v118
	v_mul_f32_e32 v119, v221, v119
	v_mul_f32_e32 v104, v223, v104
	v_mul_f32_e32 v105, v223, v105
	v_mul_f32_e32 v106, v223, v106
	v_mul_f32_e32 v107, v223, v107
	v_mul_f32_e32 v108, v223, v108
	v_mul_f32_e32 v109, v223, v109
	v_mul_f32_e32 v110, v223, v110
	v_mul_f32_e32 v111, v223, v111
	v_mul_f32_e32 v96, v223, v96
	v_mul_f32_e32 v97, v223, v97
	v_mul_f32_e32 v98, v223, v98
	v_mul_f32_e32 v99, v223, v99
	v_mul_f32_e32 v100, v223, v100
	v_mul_f32_e32 v101, v223, v101
	v_mul_f32_e32 v102, v223, v102
	v_mul_f32_e32 v103, v223, v103
	v_mul_f32_e32 v88, v225, v88
	v_mul_f32_e32 v89, v225, v89
	v_mul_f32_e32 v90, v225, v90
	v_mul_f32_e32 v91, v225, v91
	v_mul_f32_e32 v92, v225, v92
	v_mul_f32_e32 v93, v225, v93
	v_mul_f32_e32 v94, v225, v94
	v_mul_f32_e32 v95, v225, v95
	v_mul_f32_e32 v80, v225, v80
	v_mul_f32_e32 v81, v225, v81
	v_mul_f32_e32 v82, v225, v82
	v_mul_f32_e32 v83, v225, v83
	v_mul_f32_e32 v84, v225, v84
	v_mul_f32_e32 v85, v225, v85
	v_mul_f32_e32 v86, v225, v86
	v_mul_f32_e32 v87, v225, v87
	v_mul_f32_e32 v72, v227, v72
	v_mul_f32_e32 v73, v227, v73
	v_mul_f32_e32 v74, v227, v74
	v_mul_f32_e32 v75, v227, v75
	v_mul_f32_e32 v76, v227, v76
	v_mul_f32_e32 v77, v227, v77
	v_mul_f32_e32 v78, v227, v78
	v_mul_f32_e32 v79, v227, v79
	v_mul_f32_e32 v64, v227, v64
	v_mul_f32_e32 v65, v227, v65
	v_mul_f32_e32 v66, v227, v66
	v_mul_f32_e32 v67, v227, v67
	v_mul_f32_e32 v68, v227, v68
	v_mul_f32_e32 v69, v227, v69
	v_mul_f32_e32 v70, v227, v70
	v_mul_f32_e32 v71, v227, v71
	v_mul_f32_e32 v56, v229, v56
	v_mul_f32_e32 v57, v229, v57
	v_mul_f32_e32 v58, v229, v58
	v_mul_f32_e32 v59, v229, v59
	v_mul_f32_e32 v60, v229, v60
	v_mul_f32_e32 v61, v229, v61
	v_mul_f32_e32 v62, v229, v62
	v_mul_f32_e32 v63, v229, v63
	v_mul_f32_e32 v48, v229, v48
	v_mul_f32_e32 v49, v229, v49
	v_mul_f32_e32 v50, v229, v50
	v_mul_f32_e32 v51, v229, v51
	v_mul_f32_e32 v52, v229, v52
	v_mul_f32_e32 v53, v229, v53
	v_mul_f32_e32 v54, v229, v54
	v_mul_f32_e32 v55, v229, v55
	v_mul_f32_e32 v40, v231, v40
	v_mul_f32_e32 v41, v231, v41
	v_mul_f32_e32 v42, v231, v42
	v_mul_f32_e32 v43, v231, v43
	v_mul_f32_e32 v44, v231, v44
	v_mul_f32_e32 v45, v231, v45
	v_mul_f32_e32 v46, v231, v46
	v_mul_f32_e32 v47, v231, v47
	v_mul_f32_e32 v32, v231, v32
	v_mul_f32_e32 v33, v231, v33
	v_mul_f32_e32 v34, v231, v34
	v_mul_f32_e32 v35, v231, v35
	v_mul_f32_e32 v36, v231, v36
	v_mul_f32_e32 v37, v231, v37
	v_mul_f32_e32 v38, v231, v38
	v_mul_f32_e32 v39, v231, v39
	v_mul_f32_e32 v24, v233, v24
	v_mul_f32_e32 v25, v233, v25
	v_mul_f32_e32 v26, v233, v26
	v_mul_f32_e32 v27, v233, v27
	v_mul_f32_e32 v28, v233, v28
	v_mul_f32_e32 v29, v233, v29
	v_mul_f32_e32 v30, v233, v30
	v_mul_f32_e32 v31, v233, v31
	v_mul_f32_e32 v16, v233, v16
	v_mul_f32_e32 v17, v233, v17
	v_mul_f32_e32 v18, v233, v18
	v_mul_f32_e32 v19, v233, v19
	v_mul_f32_e32 v20, v233, v20
	v_mul_f32_e32 v21, v233, v21
	v_mul_f32_e32 v22, v233, v22
	v_mul_f32_e32 v23, v233, v23
	v_mul_f32_e32 v8, v235, v8
	v_mul_f32_e32 v9, v235, v9
	v_mul_f32_e32 v10, v235, v10
	v_mul_f32_e32 v11, v235, v11
	v_mul_f32_e32 v12, v235, v12
	v_mul_f32_e32 v13, v235, v13
	v_mul_f32_e32 v14, v235, v14
	v_mul_f32_e32 v15, v235, v15
	v_mul_f32_e32 v0, v235, v0
	v_mul_f32_e32 v1, v235, v1
	v_mul_f32_e32 v2, v235, v2
	v_mul_f32_e32 v3, v235, v3
	v_mul_f32_e32 v4, v235, v4
	v_mul_f32_e32 v5, v235, v5
	v_mul_f32_e32 v6, v235, v6
	v_mul_f32_e32 v7, v235, v7
	s_barrier
	v_readlane_b32 s4, v255, 51
	v_readlane_b32 s1, v255, 52
	v_readlane_b32 s5, v255, 6
	v_and_b32_e32 v176, 15, v195
	v_lshrrev_b32_e32 v177, 4, v195
	s_lshr_b32 s6, s5, 2
	s_and_b32 s7, s5, 3
	s_lshl_b32 s6, s6, 6
	v_add_u32_e32 v178, s6, v176
	v_mul_u32_u24_e32 v178, 0x410, v178
	s_lshl_b32 s7, s7, 7
	v_lshl_add_u32 v178, v177, 4, v178
	v_add_u32_e32 v178, s7, v178
	s_lshl_b32 s7, s5, 4
	v_lshlrev_b32_e32 v179, 4, v195
	s_mul_i32 s6, s7, 0x410
	v_add_u32_e32 v180, s6, v179
	s_lshl_b32 s4, s4, 8
	s_add_i32 s4, s4, s7
	s_lshl_b32 s4, s4, 12
	s_lshl_b32 s1, s1, 10
	s_add_i32 s4, s4, s1
	v_add_u32_e32 v181, s4, v179
	s_add_u32 s20, s84, 0x15aa2000
	s_addc_u32 s21, s85, 0
	s_add_u32 s24, s84, 0x19ea2000
	s_addc_u32 s25, s85, 0
	v_mov_b32_e32 v182, v181
	global_load_dwordx4 v[184:187], v182, s[20:21]
	v_add_u32_e32 v182, 0x1000, v182
	global_load_dwordx4 v[188:191], v182, s[20:21]
	v_add_u32_e32 v182, 0x1000, v182
	global_load_dwordx4 v[196:199], v182, s[20:21]
	v_add_u32_e32 v182, 0x1000, v182
	global_load_dwordx4 v[200:203], v182, s[20:21]
	v_add_u32_e32 v182, 0x1000, v182
	global_load_dwordx4 v[204:207], v182, s[20:21]
	v_add_u32_e32 v182, 0x1000, v182
	global_load_dwordx4 v[208:211], v182, s[20:21]
	v_add_u32_e32 v182, 0x1000, v182
	global_load_dwordx4 v[212:215], v182, s[20:21]
	v_add_u32_e32 v182, 0x1000, v182
	global_load_dwordx4 v[216:219], v182, s[20:21]
	v_add_u32_e32 v182, 0x1000, v182
	global_load_dwordx4 v[220:223], v182, s[20:21]
	v_add_u32_e32 v182, 0x1000, v182
	global_load_dwordx4 v[224:227], v182, s[20:21]
	v_add_u32_e32 v182, 0x1000, v182
	global_load_dwordx4 v[228:231], v182, s[20:21]
	v_add_u32_e32 v182, 0x1000, v182
	global_load_dwordx4 v[232:235], v182, s[20:21]
	v_add_u32_e32 v182, 0x1000, v182
	global_load_dwordx4 v[236:239], v182, s[20:21]
	v_add_u32_e32 v182, 0x1000, v182
	global_load_dwordx4 v[240:243], v182, s[20:21]
	v_add_u32_e32 v182, 0x1000, v182
	global_load_dwordx4 v[244:247], v182, s[20:21]
	v_add_u32_e32 v182, 0x1000, v182
	global_load_dwordx4 v[248:251], v182, s[20:21]
	ds_write_b128 v178, v[120:123]
	ds_write_b128 v178, v[124:127] offset:64
	ds_write_b128 v178, v[104:107] offset:16640
	ds_write_b128 v178, v[108:111] offset:16704
	ds_write_b128 v178, v[88:91] offset:33280
	ds_write_b128 v178, v[92:95] offset:33344
	ds_write_b128 v178, v[72:75] offset:49920
	ds_write_b128 v178, v[76:79] offset:49984
	ds_write_b128 v178, v[112:115] offset:512
	ds_write_b128 v178, v[116:119] offset:576
	ds_write_b128 v178, v[96:99] offset:17152
	ds_write_b128 v178, v[100:103] offset:17216
	ds_write_b128 v178, v[80:83] offset:33792
	ds_write_b128 v178, v[84:87] offset:33856
	ds_write_b128 v178, v[64:67] offset:50432
	ds_write_b128 v178, v[68:71] offset:50496
	s_waitcnt lgkmcnt(0)
	s_barrier
;     ...
;       if (EPI == 1) {
; #pragma unroll
;         for (int r = 0; r < 4; ++r) {
;           const int row = m0 + wm * 64 + mf * 16 + 4 * g + r;
; #pragma unroll
;           for (int nf = 0; nf < 4; ++nf) {
;             const int col = n0 + wn * 64 + nf * 16 + l15;
;             rvv[r][nf] = resid ? resid[(size_t)row * 1024 + col] : xrow(p, row)[col];
;           }
;         }
;       }
; #pragma unroll
;       for (int r = 0; r < 4; ++r) {
;         const int row = m0 + wm * 64 + mf * 16 + 4 * g + r;
;         if (EPI == 0) {
;           u16* proj = (u16*)(p.ws + OFF_PROJ) + (size_t)row * PROJ_LD;
;           if (n0 < 2048) {
;             const float2* rope = (const float2*)(p.ws + OFF_ROPE);
;             const int pi = row < NPROMPT ? (row & 2047) : 2048 + ((row - NPROMPT) & 7);
; #pragma unroll
;             for (int np = 0; np < 2; ++np) {
;               const int pc = n0 + wn * 64 + np * 32;
;               const int i = ((pc & 255) >> 5) * 16 + l15;
;               const float2 cs = rope[pi * 128 + i];
;               const float x1 = acc[mf][2 * np][r], x2 = acc[mf][2 * np + 1][r];
;               float y1 = x1 * cs.x - x2 * cs.y, y2 = x1 * cs.y + x2 * cs.x;
;               if (pc >= 1024) { y1 *= 0.0625f; y2 *= 0.0625f; }
;               const int f1 = (pc & ~255) + i;
;               proj[f1] = f2bf(y1);
;               proj[f1 + 128] = f2bf(y2);
;             }
;           } else {
; #pragma unroll
;             for (int nf = 0; nf < 4; ++nf) proj[n0 + wn * 64 + nf * 16 + l15] = f2bf(acc[mf][nf][r]);
;           }
;         } else if (EPI == 1) {
; #pragma unroll
;           for (int nf = 0; nf < 4; ++nf) {
;             const int col = n0 + wn * 64 + nf * 16 + l15;
;             const float a = (NH > 0) ? accT[mf][nf][r] : acc[mf][nf][r];
;             outf[(size_t)row * 1024 + col] = rvv[r][nf] + a;
;           }
	ds_read_b128 v[64:67], v180
	ds_read_b128 v[68:71], v180 offset:1040
	ds_read_b128 v[72:75], v180 offset:2080
	ds_read_b128 v[76:79], v180 offset:3120
	ds_read_b128 v[80:83], v180 offset:4160
	ds_read_b128 v[84:87], v180 offset:5200
	ds_read_b128 v[88:91], v180 offset:6240
	ds_read_b128 v[92:95], v180 offset:7280
	ds_read_b128 v[96:99], v180 offset:8320
	ds_read_b128 v[100:103], v180 offset:9360
	ds_read_b128 v[104:107], v180 offset:10400
	ds_read_b128 v[108:111], v180 offset:11440
	ds_read_b128 v[112:115], v180 offset:12480
	ds_read_b128 v[116:119], v180 offset:13520
	ds_read_b128 v[120:123], v180 offset:14560
	ds_read_b128 v[124:127], v180 offset:15600
	s_waitcnt lgkmcnt(0)
	s_barrier
	v_mov_b32_e32 v182, v181
	s_waitcnt vmcnt(15)
	v_add_f32_e32 v64, v64, v184
	v_add_f32_e32 v65, v65, v185
	v_add_f32_e32 v66, v66, v186
	v_add_f32_e32 v67, v67, v187
	global_store_dwordx4 v182, v[64:67], s[24:25]
	v_add_u32_e32 v182, 0x1000, v182
	s_waitcnt vmcnt(15)
	v_add_f32_e32 v68, v68, v188
	v_add_f32_e32 v69, v69, v189
	v_add_f32_e32 v70, v70, v190
	v_add_f32_e32 v71, v71, v191
	global_store_dwordx4 v182, v[68:71], s[24:25]
	v_add_u32_e32 v182, 0x1000, v182
	s_waitcnt vmcnt(15)
	v_add_f32_e32 v72, v72, v196
	v_add_f32_e32 v73, v73, v197
	v_add_f32_e32 v74, v74, v198
	v_add_f32_e32 v75, v75, v199
	global_store_dwordx4 v182, v[72:75], s[24:25]
	v_add_u32_e32 v182, 0x1000, v182
	s_waitcnt vmcnt(15)
	v_add_f32_e32 v76, v76, v200
	v_add_f32_e32 v77, v77, v201
	v_add_f32_e32 v78, v78, v202
	v_add_f32_e32 v79, v79, v203
	global_store_dwordx4 v182, v[76:79], s[24:25]
	v_add_u32_e32 v182, 0x1000, v182
	s_waitcnt vmcnt(15)
	v_add_f32_e32 v80, v80, v204
	v_add_f32_e32 v81, v81, v205
	v_add_f32_e32 v82, v82, v206
	v_add_f32_e32 v83, v83, v207
	global_store_dwordx4 v182, v[80:83], s[24:25]
	v_add_u32_e32 v182, 0x1000, v182
	s_waitcnt vmcnt(15)
	v_add_f32_e32 v84, v84, v208
	v_add_f32_e32 v85, v85, v209
	v_add_f32_e32 v86, v86, v210
	v_add_f32_e32 v87, v87, v211
	global_store_dwordx4 v182, v[84:87], s[24:25]
	v_add_u32_e32 v182, 0x1000, v182
	s_waitcnt vmcnt(15)
	v_add_f32_e32 v88, v88, v212
	v_add_f32_e32 v89, v89, v213
	v_add_f32_e32 v90, v90, v214
	v_add_f32_e32 v91, v91, v215
	global_store_dwordx4 v182, v[88:91], s[24:25]
	v_add_u32_e32 v182, 0x1000, v182
	s_waitcnt vmcnt(15)
	v_add_f32_e32 v92, v92, v216
	v_add_f32_e32 v93, v93, v217
	v_add_f32_e32 v94, v94, v218
	v_add_f32_e32 v95, v95, v219
	global_store_dwordx4 v182, v[92:95], s[24:25]
	v_add_u32_e32 v182, 0x1000, v182
	s_waitcnt vmcnt(15)
	v_add_f32_e32 v96, v96, v220
	v_add_f32_e32 v97, v97, v221
	v_add_f32_e32 v98, v98, v222
	v_add_f32_e32 v99, v99, v223
	global_store_dwordx4 v182, v[96:99], s[24:25]
	v_add_u32_e32 v182, 0x1000, v182
	s_waitcnt vmcnt(15)
	v_add_f32_e32 v100, v100, v224
	v_add_f32_e32 v101, v101, v225
	v_add_f32_e32 v102, v102, v226
	v_add_f32_e32 v103, v103, v227
	global_store_dwordx4 v182, v[100:103], s[24:25]
	v_add_u32_e32 v182, 0x1000, v182
	s_waitcnt vmcnt(15)
	v_add_f32_e32 v104, v104, v228
	v_add_f32_e32 v105, v105, v229
	v_add_f32_e32 v106, v106, v230
	v_add_f32_e32 v107, v107, v231
	global_store_dwordx4 v182, v[104:107], s[24:25]
	v_add_u32_e32 v182, 0x1000, v182
	s_waitcnt vmcnt(15)
	v_add_f32_e32 v108, v108, v232
	v_add_f32_e32 v109, v109, v233
	v_add_f32_e32 v110, v110, v234
	v_add_f32_e32 v111, v111, v235
	global_store_dwordx4 v182, v[108:111], s[24:25]
	v_add_u32_e32 v182, 0x1000, v182
	s_waitcnt vmcnt(15)
	v_add_f32_e32 v112, v112, v236
	v_add_f32_e32 v113, v113, v237
	v_add_f32_e32 v114, v114, v238
	v_add_f32_e32 v115, v115, v239
	global_store_dwordx4 v182, v[112:115], s[24:25]
	v_add_u32_e32 v182, 0x1000, v182
	s_waitcnt vmcnt(15)
	v_add_f32_e32 v116, v116, v240
	v_add_f32_e32 v117, v117, v241
	v_add_f32_e32 v118, v118, v242
	v_add_f32_e32 v119, v119, v243
	global_store_dwordx4 v182, v[116:119], s[24:25]
	v_add_u32_e32 v182, 0x1000, v182
	s_waitcnt vmcnt(15)
	v_add_f32_e32 v120, v120, v244
	v_add_f32_e32 v121, v121, v245
	v_add_f32_e32 v122, v122, v246
	v_add_f32_e32 v123, v123, v247
	global_store_dwordx4 v182, v[120:123], s[24:25]
	v_add_u32_e32 v182, 0x1000, v182
	s_waitcnt vmcnt(15)
	v_add_f32_e32 v124, v124, v248
	v_add_f32_e32 v125, v125, v249
	v_add_f32_e32 v126, v126, v250
	v_add_f32_e32 v127, v127, v251
	global_store_dwordx4 v182, v[124:127], s[24:25]
	v_add_u32_e32 v181, 0x80000, v181
	v_mov_b32_e32 v182, v181
	global_load_dwordx4 v[184:187], v182, s[20:21]
	v_add_u32_e32 v182, 0x1000, v182
	global_load_dwordx4 v[188:191], v182, s[20:21]
	v_add_u32_e32 v182, 0x1000, v182
	global_load_dwordx4 v[196:199], v182, s[20:21]
	v_add_u32_e32 v182, 0x1000, v182
	global_load_dwordx4 v[200:203], v182, s[20:21]
	v_add_u32_e32 v182, 0x1000, v182
	global_load_dwordx4 v[204:207], v182, s[20:21]
	v_add_u32_e32 v182, 0x1000, v182
	global_load_dwordx4 v[208:211], v182, s[20:21]
	v_add_u32_e32 v182, 0x1000, v182
	global_load_dwordx4 v[212:215], v182, s[20:21]
	v_add_u32_e32 v182, 0x1000, v182
	global_load_dwordx4 v[216:219], v182, s[20:21]
	v_add_u32_e32 v182, 0x1000, v182
	global_load_dwordx4 v[220:223], v182, s[20:21]
	v_add_u32_e32 v182, 0x1000, v182
	global_load_dwordx4 v[224:227], v182, s[20:21]
	v_add_u32_e32 v182, 0x1000, v182
	global_load_dwordx4 v[228:231], v182, s[20:21]
	v_add_u32_e32 v182, 0x1000, v182
	global_load_dwordx4 v[232:235], v182, s[20:21]
	v_add_u32_e32 v182, 0x1000, v182
	global_load_dwordx4 v[236:239], v182, s[20:21]
	v_add_u32_e32 v182, 0x1000, v182
	global_load_dwordx4 v[240:243], v182, s[20:21]
	v_add_u32_e32 v182, 0x1000, v182
	global_load_dwordx4 v[244:247], v182, s[20:21]
	v_add_u32_e32 v182, 0x1000, v182
	global_load_dwordx4 v[248:251], v182, s[20:21]
	ds_write_b128 v178, v[56:59]
	ds_write_b128 v178, v[60:63] offset:64
	ds_write_b128 v178, v[40:43] offset:16640
	ds_write_b128 v178, v[44:47] offset:16704
	ds_write_b128 v178, v[24:27] offset:33280
	ds_write_b128 v178, v[28:31] offset:33344
	ds_write_b128 v178, v[8:11] offset:49920
	ds_write_b128 v178, v[12:15] offset:49984
	ds_write_b128 v178, v[48:51] offset:512
	ds_write_b128 v178, v[52:55] offset:576
	ds_write_b128 v178, v[32:35] offset:17152
	ds_write_b128 v178, v[36:39] offset:17216
	ds_write_b128 v178, v[16:19] offset:33792
	ds_write_b128 v178, v[20:23] offset:33856
	ds_write_b128 v178, v[0:3] offset:50432
	ds_write_b128 v178, v[4:7] offset:50496
	s_waitcnt lgkmcnt(0)
	s_barrier
;     ...
;   for (int tile0 = rev ? (int)(gridDim.x - 1 - blockIdx.x) : (int)blockIdx.x; tile0 < ntiles * rep; tile0 += gridDim.x) {
;     const int tile = tile0 % ntiles;
;     int mt = tile / NT, nt = tile - mt * NT + nt0;
;     ...
;       if (EPI == 1) {
; #pragma unroll
;         for (int r = 0; r < 4; ++r) {
;           const int row = m0 + wm * 64 + mf * 16 + 4 * g + r;
; #pragma unroll
;           for (int nf = 0; nf < 4; ++nf) {
;             const int col = n0 + wn * 64 + nf * 16 + l15;
;             rvv[r][nf] = resid ? resid[(size_t)row * 1024 + col] : xrow(p, row)[col];
;           }
;         }
;       }
; #pragma unroll
;       for (int r = 0; r < 4; ++r) {
;         const int row = m0 + wm * 64 + mf * 16 + 4 * g + r;
;         if (EPI == 0) {
;           u16* proj = (u16*)(p.ws + OFF_PROJ) + (size_t)row * PROJ_LD;
;           if (n0 < 2048) {
;             const float2* rope = (const float2*)(p.ws + OFF_ROPE);
;             const int pi = row < NPROMPT ? (row & 2047) : 2048 + ((row - NPROMPT) & 7);
; #pragma unroll
;             for (int np = 0; np < 2; ++np) {
;               const int pc = n0 + wn * 64 + np * 32;
;               const int i = ((pc & 255) >> 5) * 16 + l15;
;               const float2 cs = rope[pi * 128 + i];
;               const float x1 = acc[mf][2 * np][r], x2 = acc[mf][2 * np + 1][r];
;               float y1 = x1 * cs.x - x2 * cs.y, y2 = x1 * cs.y + x2 * cs.x;
;               if (pc >= 1024) { y1 *= 0.0625f; y2 *= 0.0625f; }
;               const int f1 = (pc & ~255) + i;
;               proj[f1] = f2bf(y1);
;               proj[f1 + 128] = f2bf(y2);
;             }
;           } else {
; #pragma unroll
;             for (int nf = 0; nf < 4; ++nf) proj[n0 + wn * 64 + nf * 16 + l15] = f2bf(acc[mf][nf][r]);
;           }
;         } else if (EPI == 1) {
; #pragma unroll
;           for (int nf = 0; nf < 4; ++nf) {
;             const int col = n0 + wn * 64 + nf * 16 + l15;
;             const float a = (NH > 0) ? accT[mf][nf][r] : acc[mf][nf][r];
;             outf[(size_t)row * 1024 + col] = rvv[r][nf] + a;
;           }
	ds_read_b128 v[64:67], v180
	ds_read_b128 v[68:71], v180 offset:1040
	ds_read_b128 v[72:75], v180 offset:2080
	ds_read_b128 v[76:79], v180 offset:3120
	ds_read_b128 v[80:83], v180 offset:4160
	ds_read_b128 v[84:87], v180 offset:5200
	ds_read_b128 v[88:91], v180 offset:6240
	ds_read_b128 v[92:95], v180 offset:7280
	ds_read_b128 v[96:99], v180 offset:8320
	ds_read_b128 v[100:103], v180 offset:9360
	ds_read_b128 v[104:107], v180 offset:10400
	ds_read_b128 v[108:111], v180 offset:11440
	ds_read_b128 v[112:115], v180 offset:12480
	ds_read_b128 v[116:119], v180 offset:13520
	ds_read_b128 v[120:123], v180 offset:14560
	ds_read_b128 v[124:127], v180 offset:15600
	s_waitcnt lgkmcnt(0)
	s_barrier
	v_mov_b32_e32 v182, v181
	s_waitcnt vmcnt(15)
	v_add_f32_e32 v64, v64, v184
	v_add_f32_e32 v65, v65, v185
	v_add_f32_e32 v66, v66, v186
	v_add_f32_e32 v67, v67, v187
	global_store_dwordx4 v182, v[64:67], s[24:25]
	v_add_u32_e32 v182, 0x1000, v182
	s_waitcnt vmcnt(15)
	v_add_f32_e32 v68, v68, v188
	v_add_f32_e32 v69, v69, v189
	v_add_f32_e32 v70, v70, v190
	v_add_f32_e32 v71, v71, v191
	global_store_dwordx4 v182, v[68:71], s[24:25]
	v_add_u32_e32 v182, 0x1000, v182
	s_waitcnt vmcnt(15)
	v_add_f32_e32 v72, v72, v196
	v_add_f32_e32 v73, v73, v197
	v_add_f32_e32 v74, v74, v198
	v_add_f32_e32 v75, v75, v199
	global_store_dwordx4 v182, v[72:75], s[24:25]
	v_add_u32_e32 v182, 0x1000, v182
	s_waitcnt vmcnt(15)
	v_add_f32_e32 v76, v76, v200
	v_add_f32_e32 v77, v77, v201
	v_add_f32_e32 v78, v78, v202
	v_add_f32_e32 v79, v79, v203
	global_store_dwordx4 v182, v[76:79], s[24:25]
	v_add_u32_e32 v182, 0x1000, v182
	s_waitcnt vmcnt(15)
	v_add_f32_e32 v80, v80, v204
	v_add_f32_e32 v81, v81, v205
	v_add_f32_e32 v82, v82, v206
	v_add_f32_e32 v83, v83, v207
	global_store_dwordx4 v182, v[80:83], s[24:25]
	v_add_u32_e32 v182, 0x1000, v182
	s_waitcnt vmcnt(15)
	v_add_f32_e32 v84, v84, v208
	v_add_f32_e32 v85, v85, v209
	v_add_f32_e32 v86, v86, v210
	v_add_f32_e32 v87, v87, v211
	global_store_dwordx4 v182, v[84:87], s[24:25]
	v_add_u32_e32 v182, 0x1000, v182
	s_waitcnt vmcnt(15)
	v_add_f32_e32 v88, v88, v212
	v_add_f32_e32 v89, v89, v213
	v_add_f32_e32 v90, v90, v214
	v_add_f32_e32 v91, v91, v215
	global_store_dwordx4 v182, v[88:91], s[24:25]
	v_add_u32_e32 v182, 0x1000, v182
	s_waitcnt vmcnt(15)
	v_add_f32_e32 v92, v92, v216
	v_add_f32_e32 v93, v93, v217
	v_add_f32_e32 v94, v94, v218
	v_add_f32_e32 v95, v95, v219
	global_store_dwordx4 v182, v[92:95], s[24:25]
	v_add_u32_e32 v182, 0x1000, v182
	s_waitcnt vmcnt(15)
	v_add_f32_e32 v96, v96, v220
	v_add_f32_e32 v97, v97, v221
	v_add_f32_e32 v98, v98, v222
	v_add_f32_e32 v99, v99, v223
	global_store_dwordx4 v182, v[96:99], s[24:25]
	v_add_u32_e32 v182, 0x1000, v182
	s_waitcnt vmcnt(15)
	v_add_f32_e32 v100, v100, v224
	v_add_f32_e32 v101, v101, v225
	v_add_f32_e32 v102, v102, v226
	v_add_f32_e32 v103, v103, v227
	global_store_dwordx4 v182, v[100:103], s[24:25]
	v_add_u32_e32 v182, 0x1000, v182
	s_waitcnt vmcnt(15)
	v_add_f32_e32 v104, v104, v228
	v_add_f32_e32 v105, v105, v229
	v_add_f32_e32 v106, v106, v230
	v_add_f32_e32 v107, v107, v231
	global_store_dwordx4 v182, v[104:107], s[24:25]
	v_add_u32_e32 v182, 0x1000, v182
	s_waitcnt vmcnt(15)
	v_add_f32_e32 v108, v108, v232
	v_add_f32_e32 v109, v109, v233
	v_add_f32_e32 v110, v110, v234
	v_add_f32_e32 v111, v111, v235
	global_store_dwordx4 v182, v[108:111], s[24:25]
	v_add_u32_e32 v182, 0x1000, v182
	s_waitcnt vmcnt(15)
	v_add_f32_e32 v112, v112, v236
	v_add_f32_e32 v113, v113, v237
	v_add_f32_e32 v114, v114, v238
	v_add_f32_e32 v115, v115, v239
	global_store_dwordx4 v182, v[112:115], s[24:25]
	v_add_u32_e32 v182, 0x1000, v182
	s_waitcnt vmcnt(15)
	v_add_f32_e32 v116, v116, v240
	v_add_f32_e32 v117, v117, v241
	v_add_f32_e32 v118, v118, v242
	v_add_f32_e32 v119, v119, v243
	global_store_dwordx4 v182, v[116:119], s[24:25]
	v_add_u32_e32 v182, 0x1000, v182
	s_waitcnt vmcnt(15)
	v_add_f32_e32 v120, v120, v244
	v_add_f32_e32 v121, v121, v245
	v_add_f32_e32 v122, v122, v246
	v_add_f32_e32 v123, v123, v247
	global_store_dwordx4 v182, v[120:123], s[24:25]
	v_add_u32_e32 v182, 0x1000, v182
	s_waitcnt vmcnt(15)
	v_add_f32_e32 v124, v124, v248
	v_add_f32_e32 v125, v125, v249
	v_add_f32_e32 v126, v126, v250
	v_add_f32_e32 v127, v127, v251
	global_store_dwordx4 v182, v[124:127], s[24:25]
	s_waitcnt vmcnt(0)
	s_barrier
	s_mov_b64 s[0:1], 0
	s_add_u32 s12, s84, s0
	s_addc_u32 s13, s85, s1
	v_readlane_b32 s21, v255, 6
	s_bfe_u32 s22, s90, 0x10008
	s_lshl_b32 s20, s21, 6
	s_add_i32 s22, s22, 1
	s_add_u32 s6, s12, 0x15aa2000
	s_addc_u32 s7, s13, 0
	s_add_u32 s8, s12, 0x19ea2000
	s_addc_u32 s9, s13, 0
	s_waitcnt vmcnt(1)
	v_mbcnt_lo_u32_b32 v0, -1, 0
	s_add_u32 s10, s12, 0x15662000
	v_mbcnt_hi_u32_b32 v195, -1, v0
	s_addc_u32 s11, s13, 0
	s_lshl_b32 s23, s22, 9
	s_mov_b32 s23, 0
	s_mov_b64 s[2:3], 0
	v_add_u32_e32 v196, s20, v195
	s_cmp_lt_i32 s78, s23
	v_and_b32_e32 v181, 15, v195
	s_cbranch_scc1 .LBB0_2008
	v_and_b32_e32 v0, 15, v195
	s_branch .LBB0_2009
